# v32 + hand-written SwiGLU epilogue: 8 interleaved chains per row group (no trans-hazard nops, no packing movs), -log2e and rs*rs folded per row; same f32 math, 7 VALU per output instead of ~12
# speedup vs baseline: 1.0141x; 1.0086x over previous
; #define LAS __attribute__((address_space(3)))
; __device__ __forceinline__ unsigned pk2(float lo, float hi) { return pg8::cvt_pk_bf16(lo, hi); }
;     __device__ __forceinline__ void operator()(const f32x4 (&acc)[2][2][4][2], const Unit& u, int wr, int wc, int fr, int fq) const {
;         const int row0 = u.pm * 256 + wr * 64 + fr, col0 = u.pn * 128 + wc * 32 + 8 * fq;
;         if (((volatile LAS int*)rs_lds)[256] != u.pm) panel_rs_fill(rowss, u.pm, rs_lds, (wr * 4 + wc) * 64 + fq * 16 + fr);
; #pragma unroll
;         for (int ai = 0; ai < 2; ++ai)
; #pragma unroll
;             for (int m = 0; m < 4; ++m) {
;                 const int row = row0 + ai * 128 + m * 16;
;                 const float rs = rs_lds[ai * 128 + wr * 64 + m * 16 + fr];
;                 float o[8];
; #pragma unroll
;                 for (int n = 0; n < 2; ++n)
; #pragma unroll
;                     for (int i = 0; i < 4; ++i) {
;                         const float g = acc[ai][0][m][n][i] * rs, uu = acc[ai][1][m][n][i] * rs;
;                         o[n * 4 + i] = g * __builtin_amdgcn_rcpf(1.f + __builtin_amdgcn_exp2f(-LOG2E * g)) * uu;
;                     }
;                 u32x4 w; w.x = pk2(o[0], o[1]); w.y = pk2(o[2], o[3]); w.z = pk2(o[4], o[5]); w.w = pk2(o[6], o[7]);
;                 *(u32x4*)(O + (size_t)row * DFF + col0) = w;
.LBB0_420:
	v_readlane_b32 s4, v226, 44
	v_readlane_b32 s5, v226, 45
	ds_read_b32 v152, v203
	ds_read_b32 v153, v203 offset:64
	ds_read_b32 v154, v203 offset:128
	ds_read_b32 v155, v203 offset:192
	ds_read_b32 v156, v203 offset:512
	ds_read_b32 v157, v203 offset:576
	ds_read_b32 v158, v203 offset:640
	ds_read_b32 v159, v203 offset:704
	v_lshl_or_b32 v128, s87, 7, v206
	v_add_u32_e32 v130, s40, v200
	s_movk_i32 s6, 0x1600
	v_mov_b64_e32 v[172:173], s[4:5]
	s_nop 0
	v_mad_i64_i32 v[170:171], s[4:5], v130, s6, v[172:173]
	v_lshlrev_b32_e32 v174, 1, v128
	s_nop 0
	v_add_co_u32_e32 v170, vcc, v170, v174
	s_nop 1
	v_addc_co_u32_e32 v171, vcc, 0, v171, vcc
	s_waitcnt lgkmcnt(0)
	v_mul_f32_e32 v160, 0xbfb8aa3b, v152
	v_mul_f32_e32 v161, 0xbfb8aa3b, v153
	v_mul_f32_e32 v162, 0xbfb8aa3b, v154
	v_mul_f32_e32 v163, 0xbfb8aa3b, v155
	v_mul_f32_e32 v164, 0xbfb8aa3b, v156
	v_mul_f32_e32 v165, 0xbfb8aa3b, v157
	v_mul_f32_e32 v166, 0xbfb8aa3b, v158
	v_mul_f32_e32 v167, 0xbfb8aa3b, v159
	v_mul_f32_e32 v152, v152, v152
	v_mul_f32_e32 v153, v153, v153
	v_mul_f32_e32 v154, v154, v154
	v_mul_f32_e32 v155, v155, v155
	v_mul_f32_e32 v156, v156, v156
	v_mul_f32_e32 v157, v157, v157
	v_mul_f32_e32 v158, v158, v158
	v_mul_f32_e32 v159, v159, v159
	v_mul_f32_e32 v132, v124, v160
	v_mul_f32_e32 v133, v125, v160
	v_mul_f32_e32 v134, v126, v160
	v_mul_f32_e32 v135, v127, v160
	v_mul_f32_e32 v140, v116, v160
	v_mul_f32_e32 v141, v117, v160
	v_mul_f32_e32 v142, v118, v160
	v_mul_f32_e32 v143, v119, v160
	v_exp_f32_e32 v132, v132
	v_exp_f32_e32 v133, v133
	v_exp_f32_e32 v134, v134
	v_exp_f32_e32 v135, v135
	v_exp_f32_e32 v140, v140
	v_exp_f32_e32 v141, v141
	v_exp_f32_e32 v142, v142
	v_exp_f32_e32 v143, v143
	v_mul_f32_e32 v136, v124, v120
	v_mul_f32_e32 v137, v125, v121
	v_mul_f32_e32 v138, v126, v122
	v_mul_f32_e32 v139, v127, v123
	v_mul_f32_e32 v144, v116, v112
	v_mul_f32_e32 v145, v117, v113
	v_mul_f32_e32 v146, v118, v114
	v_mul_f32_e32 v147, v119, v115
	v_add_f32_e32 v132, 1.0, v132
	v_add_f32_e32 v133, 1.0, v133
	v_add_f32_e32 v134, 1.0, v134
	v_add_f32_e32 v135, 1.0, v135
	v_add_f32_e32 v140, 1.0, v140
	v_add_f32_e32 v141, 1.0, v141
	v_add_f32_e32 v142, 1.0, v142
	v_add_f32_e32 v143, 1.0, v143
	v_rcp_f32_e32 v132, v132
	v_rcp_f32_e32 v133, v133
	v_rcp_f32_e32 v134, v134
	v_rcp_f32_e32 v135, v135
	v_rcp_f32_e32 v140, v140
	v_rcp_f32_e32 v141, v141
	v_rcp_f32_e32 v142, v142
	v_rcp_f32_e32 v143, v143
	v_mul_f32_e32 v136, v136, v152
	v_mul_f32_e32 v137, v137, v152
	v_mul_f32_e32 v138, v138, v152
	v_mul_f32_e32 v139, v139, v152
	v_mul_f32_e32 v144, v144, v152
	v_mul_f32_e32 v145, v145, v152
	v_mul_f32_e32 v146, v146, v152
	v_mul_f32_e32 v147, v147, v152
	v_mul_f32_e32 v136, v136, v132
	v_mul_f32_e32 v137, v137, v133
	v_mul_f32_e32 v138, v138, v134
	v_mul_f32_e32 v139, v139, v135
	v_mul_f32_e32 v144, v144, v140
	v_mul_f32_e32 v145, v145, v141
	v_mul_f32_e32 v146, v146, v142
	v_mul_f32_e32 v147, v147, v143
	v_mov_b32_e32 v176, v170
	v_mov_b32_e32 v177, v171
	v_cvt_pk_bf16_f32 v178, v136, v137
	v_cvt_pk_bf16_f32 v179, v138, v139
	v_cvt_pk_bf16_f32 v180, v144, v145
	v_cvt_pk_bf16_f32 v181, v146, v147
	global_store_dwordx4 v[176:177], v[178:181], off
	v_mul_f32_e32 v132, v108, v161
	v_mul_f32_e32 v133, v109, v161
	v_mul_f32_e32 v134, v110, v161
	v_mul_f32_e32 v135, v111, v161
	v_mul_f32_e32 v140, v100, v161
	v_mul_f32_e32 v141, v101, v161
	v_mul_f32_e32 v142, v102, v161
	v_mul_f32_e32 v143, v103, v161
	v_exp_f32_e32 v132, v132
	v_exp_f32_e32 v133, v133
	v_exp_f32_e32 v134, v134
	v_exp_f32_e32 v135, v135
	v_exp_f32_e32 v140, v140
	v_exp_f32_e32 v141, v141
	v_exp_f32_e32 v142, v142
	v_exp_f32_e32 v143, v143
	v_mul_f32_e32 v136, v108, v104
	v_mul_f32_e32 v137, v109, v105
	v_mul_f32_e32 v138, v110, v106
	v_mul_f32_e32 v139, v111, v107
	v_mul_f32_e32 v144, v100, v96
	v_mul_f32_e32 v145, v101, v97
	v_mul_f32_e32 v146, v102, v98
	v_mul_f32_e32 v147, v103, v99
	v_add_f32_e32 v132, 1.0, v132
	v_add_f32_e32 v133, 1.0, v133
	v_add_f32_e32 v134, 1.0, v134
	v_add_f32_e32 v135, 1.0, v135
	v_add_f32_e32 v140, 1.0, v140
	v_add_f32_e32 v141, 1.0, v141
	v_add_f32_e32 v142, 1.0, v142
	v_add_f32_e32 v143, 1.0, v143
	v_rcp_f32_e32 v132, v132
	v_rcp_f32_e32 v133, v133
	v_rcp_f32_e32 v134, v134
	v_rcp_f32_e32 v135, v135
	v_rcp_f32_e32 v140, v140
	v_rcp_f32_e32 v141, v141
	v_rcp_f32_e32 v142, v142
	v_rcp_f32_e32 v143, v143
	v_mul_f32_e32 v136, v136, v153
	v_mul_f32_e32 v137, v137, v153
	v_mul_f32_e32 v138, v138, v153
	v_mul_f32_e32 v139, v139, v153
	v_mul_f32_e32 v144, v144, v153
	v_mul_f32_e32 v145, v145, v153
	v_mul_f32_e32 v146, v146, v153
	v_mul_f32_e32 v147, v147, v153
	v_mul_f32_e32 v136, v136, v132
	v_mul_f32_e32 v137, v137, v133
	v_mul_f32_e32 v138, v138, v134
	v_mul_f32_e32 v139, v139, v135
	v_mul_f32_e32 v144, v144, v140
	v_mul_f32_e32 v145, v145, v141
	v_mul_f32_e32 v146, v146, v142
	v_mul_f32_e32 v147, v147, v143
	v_add_co_u32_e32 v176, vcc, 0x16000, v170
	s_nop 1
	v_addc_co_u32_e32 v177, vcc, 0, v171, vcc
	v_cvt_pk_bf16_f32 v178, v136, v137
	v_cvt_pk_bf16_f32 v179, v138, v139
	v_cvt_pk_bf16_f32 v180, v144, v145
	v_cvt_pk_bf16_f32 v181, v146, v147
	global_store_dwordx4 v[176:177], v[178:181], off
	v_mul_f32_e32 v132, v92, v162
	v_mul_f32_e32 v133, v93, v162
	v_mul_f32_e32 v134, v94, v162
	v_mul_f32_e32 v135, v95, v162
	v_mul_f32_e32 v140, v84, v162
	v_mul_f32_e32 v141, v85, v162
	v_mul_f32_e32 v142, v86, v162
	v_mul_f32_e32 v143, v87, v162
	v_exp_f32_e32 v132, v132
	v_exp_f32_e32 v133, v133
	v_exp_f32_e32 v134, v134
	v_exp_f32_e32 v135, v135
	v_exp_f32_e32 v140, v140
	v_exp_f32_e32 v141, v141
	v_exp_f32_e32 v142, v142
	v_exp_f32_e32 v143, v143
	v_mul_f32_e32 v136, v92, v88
; __device__ __forceinline__ unsigned pk2(float lo, float hi) { return pg8::cvt_pk_bf16(lo, hi); }
;     __device__ __forceinline__ void operator()(const f32x4 (&acc)[2][2][4][2], const Unit& u, int wr, int wc, int fr, int fq) const {
;     ...
;                 const int row = row0 + ai * 128 + m * 16;
;                 const float rs = rs_lds[ai * 128 + wr * 64 + m * 16 + fr];
;                 float o[8];
; #pragma unroll
;                 for (int n = 0; n < 2; ++n)
; #pragma unroll
;                     for (int i = 0; i < 4; ++i) {
;                         const float g = acc[ai][0][m][n][i] * rs, uu = acc[ai][1][m][n][i] * rs;
;                         o[n * 4 + i] = g * __builtin_amdgcn_rcpf(1.f + __builtin_amdgcn_exp2f(-LOG2E * g)) * uu;
;                     }
;                 u32x4 w; w.x = pk2(o[0], o[1]); w.y = pk2(o[2], o[3]); w.z = pk2(o[4], o[5]); w.w = pk2(o[6], o[7]);
;                 *(u32x4*)(O + (size_t)row * DFF + col0) = w;
	v_mul_f32_e32 v137, v93, v89
	v_mul_f32_e32 v138, v94, v90
	v_mul_f32_e32 v139, v95, v91
	v_mul_f32_e32 v144, v84, v80
	v_mul_f32_e32 v145, v85, v81
	v_mul_f32_e32 v146, v86, v82
	v_mul_f32_e32 v147, v87, v83
	v_add_f32_e32 v132, 1.0, v132
	v_add_f32_e32 v133, 1.0, v133
	v_add_f32_e32 v134, 1.0, v134
	v_add_f32_e32 v135, 1.0, v135
	v_add_f32_e32 v140, 1.0, v140
	v_add_f32_e32 v141, 1.0, v141
	v_add_f32_e32 v142, 1.0, v142
	v_add_f32_e32 v143, 1.0, v143
	v_rcp_f32_e32 v132, v132
	v_rcp_f32_e32 v133, v133
	v_rcp_f32_e32 v134, v134
	v_rcp_f32_e32 v135, v135
	v_rcp_f32_e32 v140, v140
	v_rcp_f32_e32 v141, v141
	v_rcp_f32_e32 v142, v142
	v_rcp_f32_e32 v143, v143
	v_mul_f32_e32 v136, v136, v154
	v_mul_f32_e32 v137, v137, v154
	v_mul_f32_e32 v138, v138, v154
	v_mul_f32_e32 v139, v139, v154
	v_mul_f32_e32 v144, v144, v154
	v_mul_f32_e32 v145, v145, v154
	v_mul_f32_e32 v146, v146, v154
	v_mul_f32_e32 v147, v147, v154
	v_mul_f32_e32 v136, v136, v132
	v_mul_f32_e32 v137, v137, v133
	v_mul_f32_e32 v138, v138, v134
	v_mul_f32_e32 v139, v139, v135
	v_mul_f32_e32 v144, v144, v140
	v_mul_f32_e32 v145, v145, v141
	v_mul_f32_e32 v146, v146, v142
	v_mul_f32_e32 v147, v147, v143
	v_add_co_u32_e32 v176, vcc, 0x2c000, v170
	s_nop 1
	v_addc_co_u32_e32 v177, vcc, 0, v171, vcc
	v_cvt_pk_bf16_f32 v178, v136, v137
	v_cvt_pk_bf16_f32 v179, v138, v139
	v_cvt_pk_bf16_f32 v180, v144, v145
	v_cvt_pk_bf16_f32 v181, v146, v147
	global_store_dwordx4 v[176:177], v[178:181], off
	v_mul_f32_e32 v132, v76, v163
	v_mul_f32_e32 v133, v77, v163
	v_mul_f32_e32 v134, v78, v163
	v_mul_f32_e32 v135, v79, v163
	v_mul_f32_e32 v140, v68, v163
	v_mul_f32_e32 v141, v69, v163
	v_mul_f32_e32 v142, v70, v163
	v_mul_f32_e32 v143, v71, v163
	v_exp_f32_e32 v132, v132
	v_exp_f32_e32 v133, v133
	v_exp_f32_e32 v134, v134
	v_exp_f32_e32 v135, v135
	v_exp_f32_e32 v140, v140
	v_exp_f32_e32 v141, v141
	v_exp_f32_e32 v142, v142
	v_exp_f32_e32 v143, v143
	v_mul_f32_e32 v136, v76, v72
	v_mul_f32_e32 v137, v77, v73
	v_mul_f32_e32 v138, v78, v74
	v_mul_f32_e32 v139, v79, v75
	v_mul_f32_e32 v144, v68, v64
	v_mul_f32_e32 v145, v69, v65
	v_mul_f32_e32 v146, v70, v66
	v_mul_f32_e32 v147, v71, v67
	v_add_f32_e32 v132, 1.0, v132
	v_add_f32_e32 v133, 1.0, v133
	v_add_f32_e32 v134, 1.0, v134
	v_add_f32_e32 v135, 1.0, v135
	v_add_f32_e32 v140, 1.0, v140
	v_add_f32_e32 v141, 1.0, v141
	v_add_f32_e32 v142, 1.0, v142
	v_add_f32_e32 v143, 1.0, v143
	v_rcp_f32_e32 v132, v132
	v_rcp_f32_e32 v133, v133
	v_rcp_f32_e32 v134, v134
	v_rcp_f32_e32 v135, v135
	v_rcp_f32_e32 v140, v140
	v_rcp_f32_e32 v141, v141
	v_rcp_f32_e32 v142, v142
	v_rcp_f32_e32 v143, v143
	v_mul_f32_e32 v136, v136, v155
	v_mul_f32_e32 v137, v137, v155
	v_mul_f32_e32 v138, v138, v155
	v_mul_f32_e32 v139, v139, v155
	v_mul_f32_e32 v144, v144, v155
	v_mul_f32_e32 v145, v145, v155
	v_mul_f32_e32 v146, v146, v155
	v_mul_f32_e32 v147, v147, v155
	v_mul_f32_e32 v136, v136, v132
	v_mul_f32_e32 v137, v137, v133
	v_mul_f32_e32 v138, v138, v134
	v_mul_f32_e32 v139, v139, v135
	v_mul_f32_e32 v144, v144, v140
	v_mul_f32_e32 v145, v145, v141
	v_mul_f32_e32 v146, v146, v142
	v_mul_f32_e32 v147, v147, v143
	v_add_co_u32_e32 v176, vcc, 0x42000, v170
	s_nop 1
	v_addc_co_u32_e32 v177, vcc, 0, v171, vcc
	v_cvt_pk_bf16_f32 v178, v136, v137
	v_cvt_pk_bf16_f32 v179, v138, v139
	v_cvt_pk_bf16_f32 v180, v144, v145
	v_cvt_pk_bf16_f32 v181, v146, v147
	global_store_dwordx4 v[176:177], v[178:181], off
	v_mul_f32_e32 v132, v60, v164
	v_mul_f32_e32 v133, v61, v164
	v_mul_f32_e32 v134, v62, v164
	v_mul_f32_e32 v135, v63, v164
	v_mul_f32_e32 v140, v52, v164
	v_mul_f32_e32 v141, v53, v164
	v_mul_f32_e32 v142, v54, v164
	v_mul_f32_e32 v143, v55, v164
	v_exp_f32_e32 v132, v132
	v_exp_f32_e32 v133, v133
	v_exp_f32_e32 v134, v134
	v_exp_f32_e32 v135, v135
	v_exp_f32_e32 v140, v140
	v_exp_f32_e32 v141, v141
	v_exp_f32_e32 v142, v142
	v_exp_f32_e32 v143, v143
	v_mul_f32_e32 v136, v60, v56
	v_mul_f32_e32 v137, v61, v57
	v_mul_f32_e32 v138, v62, v58
	v_mul_f32_e32 v139, v63, v59
	v_mul_f32_e32 v144, v52, v48
	v_mul_f32_e32 v145, v53, v49
	v_mul_f32_e32 v146, v54, v50
	v_mul_f32_e32 v147, v55, v51
	v_add_f32_e32 v132, 1.0, v132
	v_add_f32_e32 v133, 1.0, v133
	v_add_f32_e32 v134, 1.0, v134
	v_add_f32_e32 v135, 1.0, v135
	v_add_f32_e32 v140, 1.0, v140
	v_add_f32_e32 v141, 1.0, v141
	v_add_f32_e32 v142, 1.0, v142
	v_add_f32_e32 v143, 1.0, v143
	v_rcp_f32_e32 v132, v132
	v_rcp_f32_e32 v133, v133
	v_rcp_f32_e32 v134, v134
	v_rcp_f32_e32 v135, v135
	v_rcp_f32_e32 v140, v140
	v_rcp_f32_e32 v141, v141
	v_rcp_f32_e32 v142, v142
	v_rcp_f32_e32 v143, v143
	v_mul_f32_e32 v136, v136, v156
	v_mul_f32_e32 v137, v137, v156
	v_mul_f32_e32 v138, v138, v156
	v_mul_f32_e32 v139, v139, v156
	v_mul_f32_e32 v144, v144, v156
	v_mul_f32_e32 v145, v145, v156
	v_mul_f32_e32 v146, v146, v156
	v_mul_f32_e32 v147, v147, v156
	v_mul_f32_e32 v136, v136, v132
	v_mul_f32_e32 v137, v137, v133
	v_mul_f32_e32 v138, v138, v134
	v_mul_f32_e32 v139, v139, v135
	v_mul_f32_e32 v144, v144, v140
	v_mul_f32_e32 v145, v145, v141
	v_mul_f32_e32 v146, v146, v142
	v_mul_f32_e32 v147, v147, v143
	v_add_co_u32_e32 v176, vcc, 0xb0000, v170
	s_nop 1
	v_addc_co_u32_e32 v177, vcc, 0, v171, vcc
	v_cvt_pk_bf16_f32 v178, v136, v137
	v_cvt_pk_bf16_f32 v179, v138, v139
	v_cvt_pk_bf16_f32 v180, v144, v145
	v_cvt_pk_bf16_f32 v181, v146, v147
	global_store_dwordx4 v[176:177], v[178:181], off
	v_mul_f32_e32 v132, v44, v165
	v_mul_f32_e32 v133, v45, v165
	v_mul_f32_e32 v134, v46, v165
	v_mul_f32_e32 v135, v47, v165
	v_mul_f32_e32 v140, v36, v165
	v_mul_f32_e32 v141, v37, v165
	v_mul_f32_e32 v142, v38, v165
	v_mul_f32_e32 v143, v39, v165
; __device__ __forceinline__ unsigned pk2(float lo, float hi) { return pg8::cvt_pk_bf16(lo, hi); }
;     __device__ __forceinline__ void operator()(const f32x4 (&acc)[2][2][4][2], const Unit& u, int wr, int wc, int fr, int fq) const {
;     ...
;                 const int row = row0 + ai * 128 + m * 16;
;                 const float rs = rs_lds[ai * 128 + wr * 64 + m * 16 + fr];
;                 float o[8];
; #pragma unroll
;                 for (int n = 0; n < 2; ++n)
; #pragma unroll
;                     for (int i = 0; i < 4; ++i) {
;                         const float g = acc[ai][0][m][n][i] * rs, uu = acc[ai][1][m][n][i] * rs;
;                         o[n * 4 + i] = g * __builtin_amdgcn_rcpf(1.f + __builtin_amdgcn_exp2f(-LOG2E * g)) * uu;
;                     }
;                 u32x4 w; w.x = pk2(o[0], o[1]); w.y = pk2(o[2], o[3]); w.z = pk2(o[4], o[5]); w.w = pk2(o[6], o[7]);
;                 *(u32x4*)(O + (size_t)row * DFF + col0) = w;
	v_exp_f32_e32 v132, v132
	v_exp_f32_e32 v133, v133
	v_exp_f32_e32 v134, v134
	v_exp_f32_e32 v135, v135
	v_exp_f32_e32 v140, v140
	v_exp_f32_e32 v141, v141
	v_exp_f32_e32 v142, v142
	v_exp_f32_e32 v143, v143
	v_mul_f32_e32 v136, v44, v40
	v_mul_f32_e32 v137, v45, v41
	v_mul_f32_e32 v138, v46, v42
	v_mul_f32_e32 v139, v47, v43
	v_mul_f32_e32 v144, v36, v32
	v_mul_f32_e32 v145, v37, v33
	v_mul_f32_e32 v146, v38, v34
	v_mul_f32_e32 v147, v39, v35
	v_add_f32_e32 v132, 1.0, v132
	v_add_f32_e32 v133, 1.0, v133
	v_add_f32_e32 v134, 1.0, v134
	v_add_f32_e32 v135, 1.0, v135
	v_add_f32_e32 v140, 1.0, v140
	v_add_f32_e32 v141, 1.0, v141
	v_add_f32_e32 v142, 1.0, v142
	v_add_f32_e32 v143, 1.0, v143
	v_rcp_f32_e32 v132, v132
	v_rcp_f32_e32 v133, v133
	v_rcp_f32_e32 v134, v134
	v_rcp_f32_e32 v135, v135
	v_rcp_f32_e32 v140, v140
	v_rcp_f32_e32 v141, v141
	v_rcp_f32_e32 v142, v142
	v_rcp_f32_e32 v143, v143
	v_mul_f32_e32 v136, v136, v157
	v_mul_f32_e32 v137, v137, v157
	v_mul_f32_e32 v138, v138, v157
	v_mul_f32_e32 v139, v139, v157
	v_mul_f32_e32 v144, v144, v157
	v_mul_f32_e32 v145, v145, v157
	v_mul_f32_e32 v146, v146, v157
	v_mul_f32_e32 v147, v147, v157
	v_mul_f32_e32 v136, v136, v132
	v_mul_f32_e32 v137, v137, v133
	v_mul_f32_e32 v138, v138, v134
	v_mul_f32_e32 v139, v139, v135
	v_mul_f32_e32 v144, v144, v140
	v_mul_f32_e32 v145, v145, v141
	v_mul_f32_e32 v146, v146, v142
	v_mul_f32_e32 v147, v147, v143
	v_add_co_u32_e32 v176, vcc, 0xc6000, v170
	s_nop 1
	v_addc_co_u32_e32 v177, vcc, 0, v171, vcc
	v_cvt_pk_bf16_f32 v178, v136, v137
	v_cvt_pk_bf16_f32 v179, v138, v139
	v_cvt_pk_bf16_f32 v180, v144, v145
	v_cvt_pk_bf16_f32 v181, v146, v147
	global_store_dwordx4 v[176:177], v[178:181], off
	v_mul_f32_e32 v132, v28, v166
	v_mul_f32_e32 v133, v29, v166
	v_mul_f32_e32 v134, v30, v166
	v_mul_f32_e32 v135, v31, v166
	v_mul_f32_e32 v140, v20, v166
	v_mul_f32_e32 v141, v21, v166
	v_mul_f32_e32 v142, v22, v166
	v_mul_f32_e32 v143, v23, v166
	v_exp_f32_e32 v132, v132
	v_exp_f32_e32 v133, v133
	v_exp_f32_e32 v134, v134
	v_exp_f32_e32 v135, v135
	v_exp_f32_e32 v140, v140
	v_exp_f32_e32 v141, v141
	v_exp_f32_e32 v142, v142
	v_exp_f32_e32 v143, v143
	v_mul_f32_e32 v136, v28, v24
	v_mul_f32_e32 v137, v29, v25
	v_mul_f32_e32 v138, v30, v26
	v_mul_f32_e32 v139, v31, v27
	v_mul_f32_e32 v144, v20, v16
	v_mul_f32_e32 v145, v21, v17
	v_mul_f32_e32 v146, v22, v18
	v_mul_f32_e32 v147, v23, v19
	v_add_f32_e32 v132, 1.0, v132
	v_add_f32_e32 v133, 1.0, v133
	v_add_f32_e32 v134, 1.0, v134
	v_add_f32_e32 v135, 1.0, v135
	v_add_f32_e32 v140, 1.0, v140
	v_add_f32_e32 v141, 1.0, v141
	v_add_f32_e32 v142, 1.0, v142
	v_add_f32_e32 v143, 1.0, v143
	v_rcp_f32_e32 v132, v132
	v_rcp_f32_e32 v133, v133
	v_rcp_f32_e32 v134, v134
	v_rcp_f32_e32 v135, v135
	v_rcp_f32_e32 v140, v140
	v_rcp_f32_e32 v141, v141
	v_rcp_f32_e32 v142, v142
	v_rcp_f32_e32 v143, v143
	v_mul_f32_e32 v136, v136, v158
	v_mul_f32_e32 v137, v137, v158
	v_mul_f32_e32 v138, v138, v158
	v_mul_f32_e32 v139, v139, v158
	v_mul_f32_e32 v144, v144, v158
	v_mul_f32_e32 v145, v145, v158
	v_mul_f32_e32 v146, v146, v158
	v_mul_f32_e32 v147, v147, v158
	v_mul_f32_e32 v136, v136, v132
	v_mul_f32_e32 v137, v137, v133
	v_mul_f32_e32 v138, v138, v134
	v_mul_f32_e32 v139, v139, v135
	v_mul_f32_e32 v144, v144, v140
	v_mul_f32_e32 v145, v145, v141
	v_mul_f32_e32 v146, v146, v142
	v_mul_f32_e32 v147, v147, v143
	v_add_co_u32_e32 v176, vcc, 0xdc000, v170
	s_nop 1
	v_addc_co_u32_e32 v177, vcc, 0, v171, vcc
	v_cvt_pk_bf16_f32 v178, v136, v137
	v_cvt_pk_bf16_f32 v179, v138, v139
	v_cvt_pk_bf16_f32 v180, v144, v145
	v_cvt_pk_bf16_f32 v181, v146, v147
	global_store_dwordx4 v[176:177], v[178:181], off
	v_mul_f32_e32 v132, v12, v167
	v_mul_f32_e32 v133, v13, v167
	v_mul_f32_e32 v134, v14, v167
	v_mul_f32_e32 v135, v15, v167
	v_mul_f32_e32 v140, v4, v167
	v_mul_f32_e32 v141, v5, v167
	v_mul_f32_e32 v142, v6, v167
	v_mul_f32_e32 v143, v7, v167
	v_exp_f32_e32 v132, v132
	v_exp_f32_e32 v133, v133
	v_exp_f32_e32 v134, v134
	v_exp_f32_e32 v135, v135
	v_exp_f32_e32 v140, v140
	v_exp_f32_e32 v141, v141
	v_exp_f32_e32 v142, v142
	v_exp_f32_e32 v143, v143
	v_mul_f32_e32 v136, v12, v8
	v_mul_f32_e32 v137, v13, v9
	v_mul_f32_e32 v138, v14, v10
	v_mul_f32_e32 v139, v15, v11
	v_mul_f32_e32 v144, v4, v0
	v_mul_f32_e32 v145, v5, v1
	v_mul_f32_e32 v146, v6, v2
	v_mul_f32_e32 v147, v7, v3
	v_add_f32_e32 v132, 1.0, v132
	v_add_f32_e32 v133, 1.0, v133
	v_add_f32_e32 v134, 1.0, v134
	v_add_f32_e32 v135, 1.0, v135
	v_add_f32_e32 v140, 1.0, v140
	v_add_f32_e32 v141, 1.0, v141
	v_add_f32_e32 v142, 1.0, v142
	v_add_f32_e32 v143, 1.0, v143
	v_rcp_f32_e32 v132, v132
	v_rcp_f32_e32 v133, v133
	v_rcp_f32_e32 v134, v134
	v_rcp_f32_e32 v135, v135
	v_rcp_f32_e32 v140, v140
	v_rcp_f32_e32 v141, v141
	v_rcp_f32_e32 v142, v142
	v_rcp_f32_e32 v143, v143
	v_mul_f32_e32 v136, v136, v159
	v_mul_f32_e32 v137, v137, v159
	v_mul_f32_e32 v138, v138, v159
	v_mul_f32_e32 v139, v139, v159
	v_mul_f32_e32 v144, v144, v159
	v_mul_f32_e32 v145, v145, v159
	v_mul_f32_e32 v146, v146, v159
	v_mul_f32_e32 v147, v147, v159
	v_mul_f32_e32 v136, v136, v132
	v_mul_f32_e32 v137, v137, v133
	v_mul_f32_e32 v138, v138, v134
	v_mul_f32_e32 v139, v139, v135
	v_mul_f32_e32 v144, v144, v140
	v_mul_f32_e32 v145, v145, v141
	v_mul_f32_e32 v146, v146, v142
	v_mul_f32_e32 v147, v147, v143
	v_add_co_u32_e32 v176, vcc, 0xf2000, v170
	s_nop 1
	v_addc_co_u32_e32 v177, vcc, 0, v171, vcc
	v_cvt_pk_bf16_f32 v178, v136, v137
	v_cvt_pk_bf16_f32 v179, v138, v139
	v_cvt_pk_bf16_f32 v180, v144, v145
	v_cvt_pk_bf16_f32 v181, v146, v147
	global_store_dwordx4 v[176:177], v[178:181], off
